# attention unit rewritten by hand: split-halves two accumulators (half the exp2), own epilogue; plus P5 epilogue hoisted loads
# speedup vs baseline: 1.0572x; 1.0040x over previous
.LBB0_209:
	s_bfe_u32 s14, s77, 0x30005
	s_lshl_b32 s15, s14, 22
	s_add_u32 s18, s31, s15
	s_addc_u32 s19, s34, 0
	s_and_b32 s12, s77, 7
	s_xor_b32 s22, s12, 15
	s_cmpk_lt_u32 s77, 0x100
	v_mov_b32_e32 v74, v165
	s_cselect_b32 s22, s12, s22
	s_bfe_u32 s24, s77, 0x20003
	v_readfirstlane_b32 s12, v74
	s_ashr_i32 s25, s12, 6
	s_lshl_b32 s29, s25, 3
	s_lshl_b32 s23, s25, 1
	s_or_b32 s53, s29, 4
	s_lshl_b32 s27, s14, 12
	s_lshl_b32 s26, s22, 2
	s_ashr_i32 s39, s12, 7
	s_lshl_b32 s12, s24, 8
	s_and_b32 s38, s23, 2
	s_bfe_u32 s54, s53, 0x20002
	s_lshl_b32 s55, s22, 8
	s_lshl_b32 s28, s14, 21
	s_add_u32 s22, s78, s15
	s_addc_u32 s23, s79, 0
	s_lshl_b32 s15, s25, 5
	s_or_b32 s14, s55, s27
	s_ashr_i32 s27, s15, 31
	s_add_u32 s14, s15, s14
	v_and_b32_e32 v168, 31, v74
	s_addc_u32 s15, s27, 0
	v_or_b32_e32 v0, s14, v168
	v_mov_b32_e32 v1, s15
	v_lshlrev_b64 v[0:1], 10, v[0:1]
	v_bfe_u32 v183, v74, 5, 1
	v_lshl_add_u64 v[0:1], s[46:47], 0, v[0:1]
	v_lshl_add_u64 v[0:1], v[0:1], 0, s[12:13]
	v_lshlrev_b32_e32 v166, 4, v183
	v_lshl_add_u64 v[0:1], v[0:1], 0, v[166:167]
	global_load_dwordx4 v[128:131], v[0:1], off offset:224
	global_load_dwordx4 v[132:135], v[0:1], off offset:192
	global_load_dwordx4 v[144:147], v[0:1], off offset:96
	global_load_dwordx4 v[148:151], v[0:1], off offset:64
	global_load_dwordx4 v[136:139], v[0:1], off offset:160
	global_load_dwordx4 v[140:143], v[0:1], off offset:128
	global_load_dwordx4 v[152:155], v[0:1], off offset:32
	global_load_dwordx4 v[156:159], v[0:1], off
	v_lshlrev_b32_e32 v2, 2, v74
	v_bfe_u32 v0, v74, 4, 2
	v_bfe_u32 v75, v74, 2, 2
	v_and_b32_e32 v2, 12, v2
	v_or_b32_e32 v5, 8, v183
	v_or_b32_e32 v76, 2, v183
	v_or_b32_e32 v6, 10, v183
	v_or_b32_e32 v7, 4, v183
	v_or_b32_e32 v8, 12, v183
	v_or_b32_e32 v9, 6, v183
	v_or_b32_e32 v10, 14, v183
	v_and_b32_e32 v1, 15, v74
	v_lshlrev_b32_e32 v3, 2, v0
	v_lshlrev_b32_e32 v4, 8, v168
	v_bitop3_b32 v11, v2, v183, v75 bitop3:0x36
	v_bitop3_b32 v5, v2, v5, v75 bitop3:0x36
	v_bitop3_b32 v12, v2, v76, v75 bitop3:0x36
	v_bitop3_b32 v6, v2, v6, v75 bitop3:0x36
	v_bitop3_b32 v7, v2, v7, v75 bitop3:0x36
	v_bitop3_b32 v8, v2, v8, v75 bitop3:0x36
	v_bitop3_b32 v9, v2, v9, v75 bitop3:0x36
	v_bitop3_b32 v2, v2, v10, v75 bitop3:0x36
	v_lshl_or_b32 v191, v11, 4, v4
	v_lshl_or_b32 v187, v5, 4, v4
	v_lshl_or_b32 v190, v12, 4, v4
	v_lshl_or_b32 v186, v6, 4, v4
	v_lshl_or_b32 v189, v7, 4, v4
	v_lshl_or_b32 v185, v8, 4, v4
	v_lshl_or_b32 v188, v9, 4, v4
	v_lshl_or_b32 v184, v2, 4, v4
	v_or_b32_e32 v2, s29, v0
	v_bitop3_b32 v4, s38, v1, v3 bitop3:0x36
	v_lshlrev_b32_e32 v2, 10, v2
	v_or_b32_e32 v0, s53, v0
	v_lshlrev_b32_e32 v4, 4, v4
	v_bitop3_b32 v1, s54, v1, v3 bitop3:0x36
	s_lshl_b32 s56, s25, 11
	v_lshlrev_b32_e32 v0, 10, v0
	v_or3_b32 v166, v4, v2, s12
	v_lshlrev_b32_e32 v1, 4, v1
	s_or_b32 s55, s56, 0x400
	v_mov_b32_e32 v171, v167
	v_or3_b32 v170, v1, v0, s12
	s_lshl_b32 s12, s24, 7
	s_add_i32 s39, s39, s26
	s_add_i32 s38, s56, 0
	s_add_i32 s57, s55, 0
	v_lshl_add_u64 v[70:71], s[22:23], 0, v[166:167]
	v_lshl_add_u64 v[64:65], s[22:23], 0, v[170:171]
	s_add_u32 s24, s22, 0x10000
	s_mov_b32 s27, 2
	v_mov_b32_e32 v72, v167
	v_mov_b32_e32 v73, v167
	s_mov_b32 s54, 0
	s_waitcnt vmcnt(0)
	s_mov_b32 vcc_hi, m0
	v_mov_b32_e32 v246, v242
	v_mov_b32_e32 v247, v243
	v_lshrrev_b32_e32 v0, 3, v74
	v_and_b32_e32 v0, 2, v0
	v_bfe_u32 v1, v74, 1, 1
	v_lshlrev_b32_e32 v3, 3, v74
	v_lshlrev_b32_e32 v4, 8, v75
	v_bitop3_b32 v5, v0, v183, v1 bitop3:0x36
	v_bitop3_b32 v0, v76, v0, v1 bitop3:0x1e
	v_and_b32_e32 v3, 8, v3
	v_lshl_or_b32 v4, v183, 10, v4
	v_lshlrev_b32_e32 v0, 4, v0
	v_or3_b32 v196, v0, v4, v3
	v_lshlrev_b32_e32 v5, 4, v5
	v_or3_b32 v195, v5, v4, v3
	v_lshlrev_b32_e32 v197, 6, v75
	v_xor_b32_e32 v194, 64, v197
	v_xor_b32_e32 v193, 0x80, v197
	v_xor_b32_e32 v192, 0xc0, v197
	s_or_b32 s53, s26, 2
	s_add_i32 s29, s26, 4
	s_add_i32 vcc_lo, s39, 1
	v_mov_b32_e32 v0, 0
	v_mov_b32_e32 v1, 0
	v_mov_b32_e32 v2, 0
	v_mov_b32_e32 v3, 0
	v_mov_b32_e32 v4, 0
	v_mov_b32_e32 v5, 0
	v_mov_b32_e32 v6, 0
	v_mov_b32_e32 v7, 0
	v_mov_b32_e32 v8, 0
	v_mov_b32_e32 v9, 0
	v_mov_b32_e32 v10, 0
	v_mov_b32_e32 v11, 0
	v_mov_b32_e32 v12, 0
	v_mov_b32_e32 v13, 0
	v_mov_b32_e32 v14, 0
	v_mov_b32_e32 v15, 0
	v_mov_b32_e32 v16, 0
	v_mov_b32_e32 v17, 0
	v_mov_b32_e32 v18, 0
	v_mov_b32_e32 v19, 0
	v_mov_b32_e32 v20, 0
	v_mov_b32_e32 v21, 0
	v_mov_b32_e32 v22, 0
	v_mov_b32_e32 v23, 0
	v_mov_b32_e32 v24, 0
	v_mov_b32_e32 v25, 0
	v_mov_b32_e32 v26, 0
	v_mov_b32_e32 v27, 0
	v_mov_b32_e32 v28, 0
	v_mov_b32_e32 v29, 0
	v_mov_b32_e32 v30, 0
	v_mov_b32_e32 v31, 0
	v_mov_b32_e32 v32, 0
	v_mov_b32_e32 v33, 0
	v_mov_b32_e32 v34, 0
	v_mov_b32_e32 v35, 0
	v_mov_b32_e32 v36, 0
	v_mov_b32_e32 v37, 0
	v_mov_b32_e32 v38, 0
	v_mov_b32_e32 v39, 0
	v_mov_b32_e32 v40, 0
	v_mov_b32_e32 v41, 0
	v_mov_b32_e32 v42, 0
	v_mov_b32_e32 v43, 0
	v_mov_b32_e32 v44, 0
	v_mov_b32_e32 v45, 0
	v_mov_b32_e32 v46, 0
	v_mov_b32_e32 v47, 0
	v_mov_b32_e32 v48, 0
	v_mov_b32_e32 v49, 0
	v_mov_b32_e32 v50, 0
	v_mov_b32_e32 v51, 0
	v_mov_b32_e32 v52, 0
	v_mov_b32_e32 v53, 0
	v_mov_b32_e32 v54, 0
	v_mov_b32_e32 v55, 0
	v_mov_b32_e32 v56, 0
	v_mov_b32_e32 v57, 0
	v_mov_b32_e32 v58, 0
	v_mov_b32_e32 v59, 0
	v_mov_b32_e32 v60, 0
	v_mov_b32_e32 v61, 0
	v_mov_b32_e32 v62, 0
	v_mov_b32_e32 v63, 0
	s_mov_b64 s[24:25], s[22:23]
	s_add_u32 s58, s22, 0x2000000
	s_addc_u32 s59, s23, 0
	s_add_i32 m0, s38, 0x0
	s_nop 0
	global_load_lds_dwordx4 v166, s[24:25]
	s_add_i32 m0, s57, 0x0
	s_nop 0
	global_load_lds_dwordx4 v170, s[24:25]
	s_add_i32 m0, s38, 0xc000
	s_nop 0
	global_load_lds_dwordx4 v166, s[58:59]
	s_add_i32 m0, s57, 0xc000
	s_nop 0
	global_load_lds_dwordx4 v170, s[58:59]
	s_add_u32 s24, s24, 0x10000
	s_addc_u32 s25, s25, 0
	s_add_u32 s58, s58, 0x10000
	s_addc_u32 s59, s59, 0
	s_add_i32 m0, s38, 0x4000
	s_nop 0
	global_load_lds_dwordx4 v166, s[24:25]
	s_add_i32 m0, s57, 0x4000
	s_nop 0
	global_load_lds_dwordx4 v170, s[24:25]
	s_add_i32 m0, s38, 0x10000
	s_nop 0
	global_load_lds_dwordx4 v166, s[58:59]
	s_add_i32 m0, s57, 0x10000
	s_nop 0
	global_load_lds_dwordx4 v170, s[58:59]
	s_add_u32 s24, s24, 0x10000
	s_addc_u32 s25, s25, 0
	s_add_u32 s58, s58, 0x10000
	s_addc_u32 s59, s59, 0
	s_mov_b32 s54, 0
	s_mov_b32 s60, 0
	s_mov_b32 s61, 0x8000
	v_mov_b32_e32 v104, 0
	v_mov_b32_e32 v105, 0
	v_mov_b32_e32 v106, 0
	v_mov_b32_e32 v107, 0
.Lata_step:
	s_add_i32 s54, s54, 1
	s_cmp_lt_i32 s54, s29
	s_cbranch_scc0 .Lata_w0
	s_waitcnt vmcnt(4)
	s_branch .Lata_w1

.Lata_w1:
	s_barrier
	s_cmp_gt_i32 s54, s53
	s_cbranch_scc1 .Lata_nodma
	s_add_i32 m0, s38, s61
	s_nop 0
	global_load_lds_dwordx4 v166, s[24:25]
	s_add_i32 m0, s57, s61
	s_nop 0
	global_load_lds_dwordx4 v170, s[24:25]
	s_add_i32 s62, s61, 0xc000
	s_add_i32 m0, s38, s62
	s_nop 0
	global_load_lds_dwordx4 v166, s[58:59]
	s_add_i32 m0, s57, s62
	s_nop 0
	global_load_lds_dwordx4 v170, s[58:59]
	s_add_u32 s24, s24, 0x10000
	s_addc_u32 s25, s25, 0
	s_add_u32 s58, s58, 0x10000
	s_addc_u32 s59, s59, 0
.Lata_nodma:
	s_cmp_gt_i32 s54, vcc_lo
	s_cbranch_scc1 .Lata_next
	v_add_u32_e32 v108, s60, v191
	v_add_u32_e32 v109, s60, v190
	v_add_u32_e32 v110, s60, v189
	v_add_u32_e32 v111, s60, v188
	v_add_u32_e32 v120, s60, v195
	v_add_u32_e32 v121, s60, v196
	v_add_u32_e32 v112, v120, v197
	v_add_u32_e32 v116, v121, v197
	v_add_u32_e32 v113, v120, v194
	v_add_u32_e32 v117, v121, v194
	v_add_u32_e32 v114, v120, v193
	v_add_u32_e32 v118, v121, v193
	v_add_u32_e32 v115, v120, v192
	v_add_u32_e32 v119, v121, v192
	ds_read_b128 v[88:91], v108
	ds_read_b128 v[92:95], v109
	ds_read_b128 v[96:99], v110
	ds_read_b128 v[100:103], v111
	s_waitcnt lgkmcnt(3)
	v_mfma_f32_32x32x16_bf16 v[64:79], v[88:91], v[156:159], 0
	s_waitcnt lgkmcnt(2)
	v_mfma_f32_32x32x16_bf16 v[64:79], v[92:95], v[152:155], v[64:79]
	s_waitcnt lgkmcnt(1)
	v_mfma_f32_32x32x16_bf16 v[64:79], v[96:99], v[148:151], v[64:79]
	s_waitcnt lgkmcnt(0)
	v_mfma_f32_32x32x16_bf16 v[64:79], v[100:103], v[144:147], v[64:79]
	ds_read_b64_tr_b16 v[88:89], v112 offset:49152
	ds_read_b64_tr_b16 v[90:91], v116 offset:51200
	ds_read_b64_tr_b16 v[92:93], v113 offset:49152
	ds_read_b64_tr_b16 v[94:95], v117 offset:51200
	ds_read_b64_tr_b16 v[96:97], v114 offset:49152
	ds_read_b64_tr_b16 v[98:99], v118 offset:51200
	ds_read_b64_tr_b16 v[100:101], v115 offset:49152
	ds_read_b64_tr_b16 v[102:103], v119 offset:51200
	s_nop 3
	v_exp_f32_e32 v64, v64
	v_exp_f32_e32 v65, v65
	v_exp_f32_e32 v66, v66
	v_exp_f32_e32 v67, v67
	v_pk_add_f32 v[104:105], v[104:105], v[64:65]
	v_pk_add_f32 v[106:107], v[106:107], v[66:67]
	v_exp_f32_e32 v68, v68
	v_exp_f32_e32 v69, v69
	v_exp_f32_e32 v70, v70
	v_exp_f32_e32 v71, v71
	v_pk_add_f32 v[104:105], v[104:105], v[68:69]
	v_pk_add_f32 v[106:107], v[106:107], v[70:71]
	v_exp_f32_e32 v72, v72
	v_exp_f32_e32 v73, v73
	v_exp_f32_e32 v74, v74
	v_exp_f32_e32 v75, v75
	v_pk_add_f32 v[104:105], v[104:105], v[72:73]
	v_pk_add_f32 v[106:107], v[106:107], v[74:75]
	v_exp_f32_e32 v76, v76
	v_exp_f32_e32 v77, v77
	v_exp_f32_e32 v78, v78
	v_exp_f32_e32 v79, v79
	v_pk_add_f32 v[104:105], v[104:105], v[76:77]
	v_pk_add_f32 v[106:107], v[106:107], v[78:79]
	v_cvt_pk_bf16_f32 v80, v64, v65
	v_cvt_pk_bf16_f32 v81, v66, v67
	v_cvt_pk_bf16_f32 v82, v68, v69
	v_cvt_pk_bf16_f32 v83, v70, v71
	v_cvt_pk_bf16_f32 v84, v72, v73
	v_cvt_pk_bf16_f32 v85, v74, v75
	v_cvt_pk_bf16_f32 v86, v76, v77
	v_cvt_pk_bf16_f32 v87, v78, v79
	s_nop 1
	s_waitcnt lgkmcnt(6)
	v_mfma_f32_32x32x16_bf16 v[0:15], v[80:83], v[88:91], v[0:15]
	ds_read_b64_tr_b16 v[88:89], v112 offset:53248
	ds_read_b64_tr_b16 v[90:91], v116 offset:55296
	s_waitcnt lgkmcnt(6)
	v_mfma_f32_32x32x16_bf16 v[16:31], v[80:83], v[92:95], v[16:31]
	ds_read_b64_tr_b16 v[92:93], v113 offset:53248
	ds_read_b64_tr_b16 v[94:95], v117 offset:55296
	s_waitcnt lgkmcnt(6)
	v_mfma_f32_32x32x16_bf16 v[32:47], v[80:83], v[96:99], v[32:47]
	ds_read_b64_tr_b16 v[96:97], v114 offset:53248
	ds_read_b64_tr_b16 v[98:99], v118 offset:55296
	s_waitcnt lgkmcnt(6)
	v_mfma_f32_32x32x16_bf16 v[48:63], v[80:83], v[100:103], v[48:63]
	ds_read_b64_tr_b16 v[100:101], v115 offset:53248
	ds_read_b64_tr_b16 v[102:103], v119 offset:55296
	s_waitcnt lgkmcnt(6)
	v_mfma_f32_32x32x16_bf16 v[0:15], v[84:87], v[88:91], v[0:15]
	s_waitcnt lgkmcnt(4)
	v_mfma_f32_32x32x16_bf16 v[16:31], v[84:87], v[92:95], v[16:31]
	s_waitcnt lgkmcnt(2)
	v_mfma_f32_32x32x16_bf16 v[32:47], v[84:87], v[96:99], v[32:47]
	s_waitcnt lgkmcnt(0)
	v_mfma_f32_32x32x16_bf16 v[48:63], v[84:87], v[100:103], v[48:63]
	ds_read_b128 v[88:91], v108 offset:8192
	ds_read_b128 v[92:95], v109 offset:8192
	ds_read_b128 v[96:99], v110 offset:8192
	ds_read_b128 v[100:103], v111 offset:8192
	s_waitcnt lgkmcnt(3)
	v_mfma_f32_32x32x16_bf16 v[64:79], v[88:91], v[156:159], 0
	s_waitcnt lgkmcnt(2)
	v_mfma_f32_32x32x16_bf16 v[64:79], v[92:95], v[152:155], v[64:79]
	s_waitcnt lgkmcnt(1)
	v_mfma_f32_32x32x16_bf16 v[64:79], v[96:99], v[148:151], v[64:79]
	s_waitcnt lgkmcnt(0)
	v_mfma_f32_32x32x16_bf16 v[64:79], v[100:103], v[144:147], v[64:79]
	ds_read_b64_tr_b16 v[88:89], v112 offset:57344
	ds_read_b64_tr_b16 v[90:91], v116 offset:59392
	ds_read_b64_tr_b16 v[92:93], v113 offset:57344
	ds_read_b64_tr_b16 v[94:95], v117 offset:59392
	ds_read_b64_tr_b16 v[96:97], v114 offset:57344
	ds_read_b64_tr_b16 v[98:99], v118 offset:59392
	ds_read_b64_tr_b16 v[100:101], v115 offset:57344
	ds_read_b64_tr_b16 v[102:103], v119 offset:59392
	s_nop 3
	v_exp_f32_e32 v64, v64
	v_exp_f32_e32 v65, v65
	v_exp_f32_e32 v66, v66
	v_exp_f32_e32 v67, v67
	v_pk_add_f32 v[104:105], v[104:105], v[64:65]
	v_pk_add_f32 v[106:107], v[106:107], v[66:67]
	v_exp_f32_e32 v68, v68
	v_exp_f32_e32 v69, v69
	v_exp_f32_e32 v70, v70
	v_exp_f32_e32 v71, v71
	v_pk_add_f32 v[104:105], v[104:105], v[68:69]
	v_pk_add_f32 v[106:107], v[106:107], v[70:71]
	v_exp_f32_e32 v72, v72
	v_exp_f32_e32 v73, v73
	v_exp_f32_e32 v74, v74
	v_exp_f32_e32 v75, v75
	v_pk_add_f32 v[104:105], v[104:105], v[72:73]
	v_pk_add_f32 v[106:107], v[106:107], v[74:75]
	v_exp_f32_e32 v76, v76
	v_exp_f32_e32 v77, v77
	v_exp_f32_e32 v78, v78
	v_exp_f32_e32 v79, v79
	v_pk_add_f32 v[104:105], v[104:105], v[76:77]
	v_pk_add_f32 v[106:107], v[106:107], v[78:79]
	v_cvt_pk_bf16_f32 v80, v64, v65
	v_cvt_pk_bf16_f32 v81, v66, v67
	v_cvt_pk_bf16_f32 v82, v68, v69
	v_cvt_pk_bf16_f32 v83, v70, v71
	v_cvt_pk_bf16_f32 v84, v72, v73
	v_cvt_pk_bf16_f32 v85, v74, v75
	v_cvt_pk_bf16_f32 v86, v76, v77
	v_cvt_pk_bf16_f32 v87, v78, v79
	s_nop 1
	s_waitcnt lgkmcnt(6)
	v_mfma_f32_32x32x16_bf16 v[0:15], v[80:83], v[88:91], v[0:15]
	ds_read_b64_tr_b16 v[88:89], v112 offset:61440
	ds_read_b64_tr_b16 v[90:91], v116 offset:63488
	s_waitcnt lgkmcnt(6)
	v_mfma_f32_32x32x16_bf16 v[16:31], v[80:83], v[92:95], v[16:31]
	ds_read_b64_tr_b16 v[92:93], v113 offset:61440
	ds_read_b64_tr_b16 v[94:95], v117 offset:63488
	s_waitcnt lgkmcnt(6)
	v_mfma_f32_32x32x16_bf16 v[32:47], v[80:83], v[96:99], v[32:47]
	ds_read_b64_tr_b16 v[96:97], v114 offset:61440
	ds_read_b64_tr_b16 v[98:99], v118 offset:63488
	s_waitcnt lgkmcnt(6)
	v_mfma_f32_32x32x16_bf16 v[48:63], v[80:83], v[100:103], v[48:63]
	ds_read_b64_tr_b16 v[100:101], v115 offset:61440
	ds_read_b64_tr_b16 v[102:103], v119 offset:63488
	s_waitcnt lgkmcnt(6)
	v_mfma_f32_32x32x16_bf16 v[0:15], v[84:87], v[88:91], v[0:15]
	s_waitcnt lgkmcnt(4)
	v_mfma_f32_32x32x16_bf16 v[16:31], v[84:87], v[92:95], v[16:31]
	s_waitcnt lgkmcnt(2)
	v_mfma_f32_32x32x16_bf16 v[32:47], v[84:87], v[96:99], v[32:47]
	s_waitcnt lgkmcnt(0)
	v_mfma_f32_32x32x16_bf16 v[48:63], v[84:87], v[100:103], v[48:63]
.Lata_next:
	s_add_i32 s60, s60, 0x4000
	s_cmp_lg_u32 s60, 0xc000
	s_cselect_b32 s60, s60, 0
	s_add_i32 s61, s61, 0x4000
	s_cmp_lg_u32 s61, 0xc000
	s_cselect_b32 s61, s61, 0
	s_cmp_lt_i32 s54, s29
	s_cbranch_scc1 .Lata_step
	v_pk_add_f32 v[104:105], v[104:105], v[106:107]
	s_nop 1
	v_add_f32_e32 v104, v104, v105
	ds_bpermute_b32 v106, v169, v104
	s_waitcnt lgkmcnt(0)
	v_add_f32_e32 v104, v104, v106
	v_rcp_f32_e32 v122, v104
	s_barrier
	v_mov_b32_e32 v198, 0
	v_mov_b32_e32 v199, 0
	v_mov_b32_e32 v200, 0
	v_mov_b32_e32 v201, 0
	v_mov_b32_e32 v202, 0
	v_mov_b32_e32 v203, 0
	v_mov_b32_e32 v204, 0
	v_mov_b32_e32 v205, 0
	v_mov_b32_e32 v206, 0
	v_mov_b32_e32 v207, 0
	v_mov_b32_e32 v208, 0
	v_mov_b32_e32 v209, 0
	v_mov_b32_e32 v210, 0
	v_mov_b32_e32 v211, 0
	v_mov_b32_e32 v212, 0
	v_mov_b32_e32 v213, 0
	v_mov_b32_e32 v214, 0
	v_mov_b32_e32 v215, 0
	v_mov_b32_e32 v216, 0
	v_mov_b32_e32 v217, 0
	v_mov_b32_e32 v218, 0
	v_mov_b32_e32 v219, 0
	v_mov_b32_e32 v220, 0
	v_mov_b32_e32 v221, 0
	v_mov_b32_e32 v222, 0
	v_mov_b32_e32 v223, 0
	v_mov_b32_e32 v224, 0
	v_mov_b32_e32 v225, 0
	v_mov_b32_e32 v226, 0
	v_mov_b32_e32 v227, 0
	v_mov_b32_e32 v228, 0
	v_mov_b32_e32 v229, 0
	v_mov_b32_e32 v230, 0
	v_mov_b32_e32 v231, 0
	v_mov_b32_e32 v232, 0
	v_mov_b32_e32 v233, 0
	v_mov_b32_e32 v234, 0
	v_mov_b32_e32 v235, 0
	v_mov_b32_e32 v236, 0
	v_mov_b32_e32 v237, 0
	v_mov_b32_e32 v238, 0
	v_mov_b32_e32 v239, 0
	v_mov_b32_e32 v240, 0
	v_mov_b32_e32 v241, 0
	v_mov_b32_e32 v242, 0
	v_mov_b32_e32 v243, 0
	v_mov_b32_e32 v244, 0
	v_mov_b32_e32 v245, 0
	v_mov_b32_e32 v144, 0
	v_mov_b32_e32 v145, 0
	v_mov_b32_e32 v146, 0
	v_mov_b32_e32 v147, 0
	v_mov_b32_e32 v148, 0
	v_mov_b32_e32 v149, 0
	v_mov_b32_e32 v150, 0
	v_mov_b32_e32 v151, 0
	v_mov_b32_e32 v152, 0
	v_mov_b32_e32 v153, 0
	v_mov_b32_e32 v154, 0
	v_mov_b32_e32 v155, 0
	v_mov_b32_e32 v156, 0
	v_mov_b32_e32 v157, 0
	v_mov_b32_e32 v158, 0
	v_mov_b32_e32 v159, 0
	s_mov_b64 s[24:25], s[22:23]
	s_add_u32 s58, s22, 0x2000000
	s_addc_u32 s59, s23, 0
	s_add_i32 m0, s38, 0x0
	s_nop 0
	global_load_lds_dwordx4 v166, s[24:25]
	s_add_i32 m0, s57, 0x0
	s_nop 0
	global_load_lds_dwordx4 v170, s[24:25]
	s_add_i32 m0, s38, 0xc000
	s_nop 0
	global_load_lds_dwordx4 v166, s[58:59]
	s_add_i32 m0, s57, 0xc000
	s_nop 0
	global_load_lds_dwordx4 v170, s[58:59]
	s_add_u32 s24, s24, 0x10000
	s_addc_u32 s25, s25, 0
	s_add_u32 s58, s58, 0x10000
	s_addc_u32 s59, s59, 0
	s_add_i32 m0, s38, 0x4000
	s_nop 0
	global_load_lds_dwordx4 v166, s[24:25]
	s_add_i32 m0, s57, 0x4000
	s_nop 0
	global_load_lds_dwordx4 v170, s[24:25]
	s_add_i32 m0, s38, 0x10000
	s_nop 0
	global_load_lds_dwordx4 v166, s[58:59]
	s_add_i32 m0, s57, 0x10000
	s_nop 0
	global_load_lds_dwordx4 v170, s[58:59]
	s_add_u32 s24, s24, 0x10000
	s_addc_u32 s25, s25, 0
	s_add_u32 s58, s58, 0x10000
	s_addc_u32 s59, s59, 0
	s_mov_b32 s54, 0
	s_mov_b32 s60, 0
	s_mov_b32 s61, 0x8000
	v_mov_b32_e32 v104, 0
	v_mov_b32_e32 v105, 0
	v_mov_b32_e32 v106, 0
	v_mov_b32_e32 v107, 0

.Latb_nodma:
	s_cmp_gt_i32 s54, vcc_lo
	s_cbranch_scc1 .Latb_next
	v_add_u32_e32 v108, s60, v187
	v_add_u32_e32 v109, s60, v186
	v_add_u32_e32 v110, s60, v185
	v_add_u32_e32 v111, s60, v184
	v_add_u32_e32 v120, s60, v195
	v_add_u32_e32 v121, s60, v196
	v_add_u32_e32 v112, v120, v197
	v_add_u32_e32 v116, v121, v197
	v_add_u32_e32 v113, v120, v194
	v_add_u32_e32 v117, v121, v194
	v_add_u32_e32 v114, v120, v193
	v_add_u32_e32 v118, v121, v193
	v_add_u32_e32 v115, v120, v192
	v_add_u32_e32 v119, v121, v192
	ds_read_b128 v[88:91], v108
	ds_read_b128 v[92:95], v109
	ds_read_b128 v[96:99], v110
	ds_read_b128 v[100:103], v111
	s_waitcnt lgkmcnt(3)
	v_mfma_f32_32x32x16_bf16 v[64:79], v[88:91], v[140:143], 0
	s_waitcnt lgkmcnt(2)
	v_mfma_f32_32x32x16_bf16 v[64:79], v[92:95], v[136:139], v[64:79]
	s_waitcnt lgkmcnt(1)
	v_mfma_f32_32x32x16_bf16 v[64:79], v[96:99], v[132:135], v[64:79]
	s_waitcnt lgkmcnt(0)
	v_mfma_f32_32x32x16_bf16 v[64:79], v[100:103], v[128:131], v[64:79]
	ds_read_b64_tr_b16 v[88:89], v112 offset:49152
	ds_read_b64_tr_b16 v[90:91], v116 offset:51200
	ds_read_b64_tr_b16 v[92:93], v113 offset:49152
	ds_read_b64_tr_b16 v[94:95], v117 offset:51200
	ds_read_b64_tr_b16 v[96:97], v114 offset:49152
	ds_read_b64_tr_b16 v[98:99], v118 offset:51200
	ds_read_b64_tr_b16 v[100:101], v115 offset:49152
	ds_read_b64_tr_b16 v[102:103], v119 offset:51200
	s_nop 3
	v_exp_f32_e32 v64, v64
	v_exp_f32_e32 v65, v65
	v_exp_f32_e32 v66, v66
	v_exp_f32_e32 v67, v67
	v_pk_add_f32 v[104:105], v[104:105], v[64:65]
	v_pk_add_f32 v[106:107], v[106:107], v[66:67]
	v_exp_f32_e32 v68, v68
	v_exp_f32_e32 v69, v69
	v_exp_f32_e32 v70, v70
	v_exp_f32_e32 v71, v71
	v_pk_add_f32 v[104:105], v[104:105], v[68:69]
	v_pk_add_f32 v[106:107], v[106:107], v[70:71]
	v_exp_f32_e32 v72, v72
	v_exp_f32_e32 v73, v73
	v_exp_f32_e32 v74, v74
	v_exp_f32_e32 v75, v75
	v_pk_add_f32 v[104:105], v[104:105], v[72:73]
	v_pk_add_f32 v[106:107], v[106:107], v[74:75]
	v_exp_f32_e32 v76, v76
	v_exp_f32_e32 v77, v77
	v_exp_f32_e32 v78, v78
	v_exp_f32_e32 v79, v79
	v_pk_add_f32 v[104:105], v[104:105], v[76:77]
	v_pk_add_f32 v[106:107], v[106:107], v[78:79]
	v_cvt_pk_bf16_f32 v80, v64, v65
	v_cvt_pk_bf16_f32 v81, v66, v67
	v_cvt_pk_bf16_f32 v82, v68, v69
	v_cvt_pk_bf16_f32 v83, v70, v71
	v_cvt_pk_bf16_f32 v84, v72, v73
	v_cvt_pk_bf16_f32 v85, v74, v75
	v_cvt_pk_bf16_f32 v86, v76, v77
	v_cvt_pk_bf16_f32 v87, v78, v79
	s_nop 1
	s_waitcnt lgkmcnt(6)
	v_mfma_f32_32x32x16_bf16 v[198:213], v[80:83], v[88:91], v[198:213]
	ds_read_b64_tr_b16 v[88:89], v112 offset:53248
	ds_read_b64_tr_b16 v[90:91], v116 offset:55296
	s_waitcnt lgkmcnt(6)
	v_mfma_f32_32x32x16_bf16 v[214:229], v[80:83], v[92:95], v[214:229]
	ds_read_b64_tr_b16 v[92:93], v113 offset:53248
	ds_read_b64_tr_b16 v[94:95], v117 offset:55296
	s_waitcnt lgkmcnt(6)
	v_mfma_f32_32x32x16_bf16 v[230:245], v[80:83], v[96:99], v[230:245]
	ds_read_b64_tr_b16 v[96:97], v114 offset:53248
	ds_read_b64_tr_b16 v[98:99], v118 offset:55296
	s_waitcnt lgkmcnt(6)
	v_mfma_f32_32x32x16_bf16 v[144:159], v[80:83], v[100:103], v[144:159]
	ds_read_b64_tr_b16 v[100:101], v115 offset:53248
	ds_read_b64_tr_b16 v[102:103], v119 offset:55296
	s_waitcnt lgkmcnt(6)
	v_mfma_f32_32x32x16_bf16 v[198:213], v[84:87], v[88:91], v[198:213]
	s_waitcnt lgkmcnt(4)
	v_mfma_f32_32x32x16_bf16 v[214:229], v[84:87], v[92:95], v[214:229]
	s_waitcnt lgkmcnt(2)
	v_mfma_f32_32x32x16_bf16 v[230:245], v[84:87], v[96:99], v[230:245]
	s_waitcnt lgkmcnt(0)
	v_mfma_f32_32x32x16_bf16 v[144:159], v[84:87], v[100:103], v[144:159]
	ds_read_b128 v[88:91], v108 offset:8192
	ds_read_b128 v[92:95], v109 offset:8192
	ds_read_b128 v[96:99], v110 offset:8192
	ds_read_b128 v[100:103], v111 offset:8192
	s_waitcnt lgkmcnt(3)
	v_mfma_f32_32x32x16_bf16 v[64:79], v[88:91], v[140:143], 0
	s_waitcnt lgkmcnt(2)
	v_mfma_f32_32x32x16_bf16 v[64:79], v[92:95], v[136:139], v[64:79]
	s_waitcnt lgkmcnt(1)
	v_mfma_f32_32x32x16_bf16 v[64:79], v[96:99], v[132:135], v[64:79]
	s_waitcnt lgkmcnt(0)
	v_mfma_f32_32x32x16_bf16 v[64:79], v[100:103], v[128:131], v[64:79]
	ds_read_b64_tr_b16 v[88:89], v112 offset:57344
	ds_read_b64_tr_b16 v[90:91], v116 offset:59392
	ds_read_b64_tr_b16 v[92:93], v113 offset:57344
	ds_read_b64_tr_b16 v[94:95], v117 offset:59392
	ds_read_b64_tr_b16 v[96:97], v114 offset:57344
	ds_read_b64_tr_b16 v[98:99], v118 offset:59392
	ds_read_b64_tr_b16 v[100:101], v115 offset:57344
	ds_read_b64_tr_b16 v[102:103], v119 offset:59392
	s_nop 3
	v_exp_f32_e32 v64, v64
	v_exp_f32_e32 v65, v65
	v_exp_f32_e32 v66, v66
	v_exp_f32_e32 v67, v67
	v_pk_add_f32 v[104:105], v[104:105], v[64:65]
	v_pk_add_f32 v[106:107], v[106:107], v[66:67]
	v_exp_f32_e32 v68, v68
	v_exp_f32_e32 v69, v69
	v_exp_f32_e32 v70, v70
	v_exp_f32_e32 v71, v71
	v_pk_add_f32 v[104:105], v[104:105], v[68:69]
	v_pk_add_f32 v[106:107], v[106:107], v[70:71]
	v_exp_f32_e32 v72, v72
	v_exp_f32_e32 v73, v73
	v_exp_f32_e32 v74, v74
	v_exp_f32_e32 v75, v75
	v_pk_add_f32 v[104:105], v[104:105], v[72:73]
	v_pk_add_f32 v[106:107], v[106:107], v[74:75]
	v_exp_f32_e32 v76, v76
	v_exp_f32_e32 v77, v77
	v_exp_f32_e32 v78, v78
	v_exp_f32_e32 v79, v79
	v_pk_add_f32 v[104:105], v[104:105], v[76:77]
	v_pk_add_f32 v[106:107], v[106:107], v[78:79]
	v_cvt_pk_bf16_f32 v80, v64, v65
	v_cvt_pk_bf16_f32 v81, v66, v67
	v_cvt_pk_bf16_f32 v82, v68, v69
	v_cvt_pk_bf16_f32 v83, v70, v71
	v_cvt_pk_bf16_f32 v84, v72, v73
	v_cvt_pk_bf16_f32 v85, v74, v75
	v_cvt_pk_bf16_f32 v86, v76, v77
	v_cvt_pk_bf16_f32 v87, v78, v79
	s_nop 1
	s_waitcnt lgkmcnt(6)
	v_mfma_f32_32x32x16_bf16 v[198:213], v[80:83], v[88:91], v[198:213]
	ds_read_b64_tr_b16 v[88:89], v112 offset:61440
	ds_read_b64_tr_b16 v[90:91], v116 offset:63488
	s_waitcnt lgkmcnt(6)
	v_mfma_f32_32x32x16_bf16 v[214:229], v[80:83], v[92:95], v[214:229]
	ds_read_b64_tr_b16 v[92:93], v113 offset:61440
	ds_read_b64_tr_b16 v[94:95], v117 offset:63488
	s_waitcnt lgkmcnt(6)
	v_mfma_f32_32x32x16_bf16 v[230:245], v[80:83], v[96:99], v[230:245]
	ds_read_b64_tr_b16 v[96:97], v114 offset:61440
	ds_read_b64_tr_b16 v[98:99], v118 offset:63488
	s_waitcnt lgkmcnt(6)
	v_mfma_f32_32x32x16_bf16 v[144:159], v[80:83], v[100:103], v[144:159]
	ds_read_b64_tr_b16 v[100:101], v115 offset:61440
	ds_read_b64_tr_b16 v[102:103], v119 offset:63488
	s_waitcnt lgkmcnt(6)
	v_mfma_f32_32x32x16_bf16 v[198:213], v[84:87], v[88:91], v[198:213]
	s_waitcnt lgkmcnt(4)
	v_mfma_f32_32x32x16_bf16 v[214:229], v[84:87], v[92:95], v[214:229]
	s_waitcnt lgkmcnt(2)
	v_mfma_f32_32x32x16_bf16 v[230:245], v[84:87], v[96:99], v[230:245]
	s_waitcnt lgkmcnt(0)
	v_mfma_f32_32x32x16_bf16 v[144:159], v[84:87], v[100:103], v[144:159]
.Latb_next:
	s_add_i32 s60, s60, 0x4000
	s_cmp_lg_u32 s60, 0xc000
	s_cselect_b32 s60, s60, 0
	s_add_i32 s61, s61, 0x4000
	s_cmp_lg_u32 s61, 0xc000
	s_cselect_b32 s61, s61, 0
	s_cmp_lt_i32 s54, s29
	s_cbranch_scc1 .Latb_step
	v_pk_add_f32 v[104:105], v[104:105], v[106:107]
	s_nop 1
	v_add_f32_e32 v104, v104, v105
	ds_bpermute_b32 v106, v169, v104
	s_waitcnt lgkmcnt(0)
	v_add_f32_e32 v104, v104, v106
	v_rcp_f32_e32 v123, v104
	s_nop 0
	v_mul_f32_e32 v123, v181, v123
	v_lshlrev_b32_e32 v64, 4, v183
	v_add_u32_e32 v98, 0, v64
	ds_bpermute_b32 v66, v98, v122
	ds_bpermute_b32 v82, v98, v123
	v_add_u32_e32 v99, 4, v64
	ds_bpermute_b32 v67, v99, v122
	ds_bpermute_b32 v83, v99, v123
	v_add_u32_e32 v100, 8, v64
	ds_bpermute_b32 v68, v100, v122
	ds_bpermute_b32 v84, v100, v123
	v_add_u32_e32 v101, 12, v64
	ds_bpermute_b32 v69, v101, v122
	ds_bpermute_b32 v85, v101, v123
	s_waitcnt lgkmcnt(0)
	v_mul_f32_e32 v198, v198, v82
	v_mul_f32_e32 v214, v214, v82
	v_mul_f32_e32 v230, v230, v82
	v_mul_f32_e32 v144, v144, v82
	v_fma_f32 v0, v0, v66, -v198
	v_fma_f32 v16, v16, v66, -v214
	v_fma_f32 v32, v32, v66, -v230
	v_fma_f32 v48, v48, v66, -v144
	v_mul_f32_e32 v199, v199, v83
	v_mul_f32_e32 v215, v215, v83
	v_mul_f32_e32 v231, v231, v83
	v_mul_f32_e32 v145, v145, v83
	v_fma_f32 v1, v1, v67, -v199
	v_fma_f32 v17, v17, v67, -v215
	v_fma_f32 v33, v33, v67, -v231
	v_fma_f32 v49, v49, v67, -v145
	v_mul_f32_e32 v200, v200, v84
	v_mul_f32_e32 v216, v216, v84
	v_mul_f32_e32 v232, v232, v84
	v_mul_f32_e32 v146, v146, v84
	v_fma_f32 v2, v2, v68, -v200
	v_fma_f32 v18, v18, v68, -v216
	v_fma_f32 v34, v34, v68, -v232
	v_fma_f32 v50, v50, v68, -v146
	v_mul_f32_e32 v201, v201, v85
	v_mul_f32_e32 v217, v217, v85
	v_mul_f32_e32 v233, v233, v85
	v_mul_f32_e32 v147, v147, v85
	v_fma_f32 v3, v3, v69, -v201
	v_fma_f32 v19, v19, v69, -v217
	v_fma_f32 v35, v35, v69, -v233
	v_fma_f32 v51, v51, v69, -v147
	v_add_u32_e32 v98, 32, v64
	ds_bpermute_b32 v70, v98, v122
	ds_bpermute_b32 v86, v98, v123
	v_add_u32_e32 v99, 36, v64
	ds_bpermute_b32 v71, v99, v122
	ds_bpermute_b32 v87, v99, v123
	v_add_u32_e32 v100, 40, v64
	ds_bpermute_b32 v72, v100, v122
	ds_bpermute_b32 v88, v100, v123
	v_add_u32_e32 v101, 44, v64
	ds_bpermute_b32 v73, v101, v122
	ds_bpermute_b32 v89, v101, v123
	s_waitcnt lgkmcnt(0)
	v_mul_f32_e32 v202, v202, v86
	v_mul_f32_e32 v218, v218, v86
	v_mul_f32_e32 v234, v234, v86
	v_mul_f32_e32 v148, v148, v86
	v_fma_f32 v4, v4, v70, -v202
	v_fma_f32 v20, v20, v70, -v218
	v_fma_f32 v36, v36, v70, -v234
	v_fma_f32 v52, v52, v70, -v148
	v_mul_f32_e32 v203, v203, v87
	v_mul_f32_e32 v219, v219, v87
	v_mul_f32_e32 v235, v235, v87
	v_mul_f32_e32 v149, v149, v87
	v_fma_f32 v5, v5, v71, -v203
	v_fma_f32 v21, v21, v71, -v219
	v_fma_f32 v37, v37, v71, -v235
	v_fma_f32 v53, v53, v71, -v149
	v_mul_f32_e32 v204, v204, v88
	v_mul_f32_e32 v220, v220, v88
	v_mul_f32_e32 v236, v236, v88
	v_mul_f32_e32 v150, v150, v88
	v_fma_f32 v6, v6, v72, -v204
	v_fma_f32 v22, v22, v72, -v220
	v_fma_f32 v38, v38, v72, -v236
	v_fma_f32 v54, v54, v72, -v150
	v_mul_f32_e32 v205, v205, v89
	v_mul_f32_e32 v221, v221, v89
	v_mul_f32_e32 v237, v237, v89
	v_mul_f32_e32 v151, v151, v89
	v_fma_f32 v7, v7, v73, -v205
	v_fma_f32 v23, v23, v73, -v221
	v_fma_f32 v39, v39, v73, -v237
	v_fma_f32 v55, v55, v73, -v151
	v_add_u32_e32 v98, 64, v64
	ds_bpermute_b32 v74, v98, v122
	ds_bpermute_b32 v90, v98, v123
	v_add_u32_e32 v99, 68, v64
	ds_bpermute_b32 v75, v99, v122
	ds_bpermute_b32 v91, v99, v123
	v_add_u32_e32 v100, 72, v64
	ds_bpermute_b32 v76, v100, v122
	ds_bpermute_b32 v92, v100, v123
	v_add_u32_e32 v101, 76, v64
	ds_bpermute_b32 v77, v101, v122
	ds_bpermute_b32 v93, v101, v123
	s_waitcnt lgkmcnt(0)
	v_mul_f32_e32 v206, v206, v90
	v_mul_f32_e32 v222, v222, v90
	v_mul_f32_e32 v238, v238, v90
	v_mul_f32_e32 v152, v152, v90
	v_fma_f32 v8, v8, v74, -v206
	v_fma_f32 v24, v24, v74, -v222
	v_fma_f32 v40, v40, v74, -v238
	v_fma_f32 v56, v56, v74, -v152
	v_mul_f32_e32 v207, v207, v91
	v_mul_f32_e32 v223, v223, v91
	v_mul_f32_e32 v239, v239, v91
	v_mul_f32_e32 v153, v153, v91
	v_fma_f32 v9, v9, v75, -v207
	v_fma_f32 v25, v25, v75, -v223
	v_fma_f32 v41, v41, v75, -v239
	v_fma_f32 v57, v57, v75, -v153
	v_mul_f32_e32 v208, v208, v92
	v_mul_f32_e32 v224, v224, v92
	v_mul_f32_e32 v240, v240, v92
	v_mul_f32_e32 v154, v154, v92
	v_fma_f32 v10, v10, v76, -v208
	v_fma_f32 v26, v26, v76, -v224
	v_fma_f32 v42, v42, v76, -v240
	v_fma_f32 v58, v58, v76, -v154
	v_mul_f32_e32 v209, v209, v93
	v_mul_f32_e32 v225, v225, v93
	v_mul_f32_e32 v241, v241, v93
	v_mul_f32_e32 v155, v155, v93
	v_fma_f32 v11, v11, v77, -v209
	v_fma_f32 v27, v27, v77, -v225
	v_fma_f32 v43, v43, v77, -v241
	v_fma_f32 v59, v59, v77, -v155
	v_add_u32_e32 v98, 96, v64
	ds_bpermute_b32 v78, v98, v122
	ds_bpermute_b32 v94, v98, v123
	v_add_u32_e32 v99, 100, v64
	ds_bpermute_b32 v79, v99, v122
	ds_bpermute_b32 v95, v99, v123
	v_add_u32_e32 v100, 104, v64
	ds_bpermute_b32 v80, v100, v122
	ds_bpermute_b32 v96, v100, v123
	v_add_u32_e32 v101, 108, v64
	ds_bpermute_b32 v81, v101, v122
	ds_bpermute_b32 v97, v101, v123
	s_waitcnt lgkmcnt(0)
	v_mul_f32_e32 v210, v210, v94
	v_mul_f32_e32 v226, v226, v94
	v_mul_f32_e32 v242, v242, v94
	v_mul_f32_e32 v156, v156, v94
	v_fma_f32 v12, v12, v78, -v210
	v_fma_f32 v28, v28, v78, -v226
	v_fma_f32 v44, v44, v78, -v242
	v_fma_f32 v60, v60, v78, -v156
	v_mul_f32_e32 v211, v211, v95
	v_mul_f32_e32 v227, v227, v95
	v_mul_f32_e32 v243, v243, v95
	v_mul_f32_e32 v157, v157, v95
	v_fma_f32 v13, v13, v79, -v211
	v_fma_f32 v29, v29, v79, -v227
	v_fma_f32 v45, v45, v79, -v243
	v_fma_f32 v61, v61, v79, -v157
	v_mul_f32_e32 v212, v212, v96
	v_mul_f32_e32 v228, v228, v96
	v_mul_f32_e32 v244, v244, v96
	v_mul_f32_e32 v158, v158, v96
	v_fma_f32 v14, v14, v80, -v212
	v_fma_f32 v30, v30, v80, -v228
	v_fma_f32 v46, v46, v80, -v244
	v_fma_f32 v62, v62, v80, -v158
	v_mul_f32_e32 v213, v213, v97
	v_mul_f32_e32 v229, v229, v97
	v_mul_f32_e32 v245, v245, v97
	v_mul_f32_e32 v159, v159, v97
	v_fma_f32 v15, v15, v81, -v213
	v_fma_f32 v31, v31, v81, -v229
	v_fma_f32 v47, v47, v81, -v245
	v_fma_f32 v63, v63, v81, -v159
	v_lshlrev_b32_e32 v64, 2, v168
	global_load_dword v100, v64, s[44:45]
	global_load_dword v101, v64, s[44:45] offset:128
	global_load_dword v102, v64, s[44:45] offset:256
	global_load_dword v103, v64, s[44:45] offset:384
	v_mul_f32_e32 v66, v0, v0
	v_fmac_f32_e32 v66, v16, v16
	v_fmac_f32_e32 v66, v32, v32
	v_fmac_f32_e32 v66, v48, v48
	v_mul_f32_e32 v67, v1, v1
	v_fmac_f32_e32 v67, v17, v17
	v_fmac_f32_e32 v67, v33, v33
	v_fmac_f32_e32 v67, v49, v49
	v_mul_f32_e32 v68, v2, v2
	v_fmac_f32_e32 v68, v18, v18
	v_fmac_f32_e32 v68, v34, v34
	v_fmac_f32_e32 v68, v50, v50
	v_mul_f32_e32 v69, v3, v3
	v_fmac_f32_e32 v69, v19, v19
	v_fmac_f32_e32 v69, v35, v35
	v_fmac_f32_e32 v69, v51, v51
	v_mul_f32_e32 v70, v4, v4
	v_fmac_f32_e32 v70, v20, v20
	v_fmac_f32_e32 v70, v36, v36
	v_fmac_f32_e32 v70, v52, v52
	v_mul_f32_e32 v71, v5, v5
	v_fmac_f32_e32 v71, v21, v21
	v_fmac_f32_e32 v71, v37, v37
	v_fmac_f32_e32 v71, v53, v53
	v_mul_f32_e32 v72, v6, v6
	v_fmac_f32_e32 v72, v22, v22
	v_fmac_f32_e32 v72, v38, v38
	v_fmac_f32_e32 v72, v54, v54
	v_mul_f32_e32 v73, v7, v7
	v_fmac_f32_e32 v73, v23, v23
	v_fmac_f32_e32 v73, v39, v39
	v_fmac_f32_e32 v73, v55, v55
	v_mul_f32_e32 v74, v8, v8
	v_fmac_f32_e32 v74, v24, v24
	v_fmac_f32_e32 v74, v40, v40
	v_fmac_f32_e32 v74, v56, v56
	v_mul_f32_e32 v75, v9, v9
	v_fmac_f32_e32 v75, v25, v25
	v_fmac_f32_e32 v75, v41, v41
	v_fmac_f32_e32 v75, v57, v57
	v_mul_f32_e32 v76, v10, v10
	v_fmac_f32_e32 v76, v26, v26
	v_fmac_f32_e32 v76, v42, v42
	v_fmac_f32_e32 v76, v58, v58
	v_mul_f32_e32 v77, v11, v11
	v_fmac_f32_e32 v77, v27, v27
	v_fmac_f32_e32 v77, v43, v43
	v_fmac_f32_e32 v77, v59, v59
	v_mul_f32_e32 v78, v12, v12
	v_fmac_f32_e32 v78, v28, v28
	v_fmac_f32_e32 v78, v44, v44
	v_fmac_f32_e32 v78, v60, v60
	v_mul_f32_e32 v79, v13, v13
	v_fmac_f32_e32 v79, v29, v29
	v_fmac_f32_e32 v79, v45, v45
	v_fmac_f32_e32 v79, v61, v61
	v_mul_f32_e32 v80, v14, v14
	v_fmac_f32_e32 v80, v30, v30
	v_fmac_f32_e32 v80, v46, v46
	v_fmac_f32_e32 v80, v62, v62
	v_mul_f32_e32 v81, v15, v15
	v_fmac_f32_e32 v81, v31, v31
	v_fmac_f32_e32 v81, v47, v47
	v_fmac_f32_e32 v81, v63, v63
	ds_bpermute_b32 v82, v177, v66
	ds_bpermute_b32 v83, v177, v67
	ds_bpermute_b32 v84, v177, v68
	ds_bpermute_b32 v85, v177, v69
	ds_bpermute_b32 v86, v177, v70
	ds_bpermute_b32 v87, v177, v71
	ds_bpermute_b32 v88, v177, v72
	ds_bpermute_b32 v89, v177, v73
	s_waitcnt lgkmcnt(7)
	v_add_f32_e32 v66, v66, v82
	s_waitcnt lgkmcnt(6)
	v_add_f32_e32 v67, v67, v83
	s_waitcnt lgkmcnt(5)
	v_add_f32_e32 v68, v68, v84
	s_waitcnt lgkmcnt(4)
	v_add_f32_e32 v69, v69, v85
	s_waitcnt lgkmcnt(3)
	v_add_f32_e32 v70, v70, v86
	s_waitcnt lgkmcnt(2)
	v_add_f32_e32 v71, v71, v87
	s_waitcnt lgkmcnt(1)
	v_add_f32_e32 v72, v72, v88
	s_waitcnt lgkmcnt(0)
	v_add_f32_e32 v73, v73, v89
	ds_bpermute_b32 v90, v177, v74
	ds_bpermute_b32 v91, v177, v75
	ds_bpermute_b32 v92, v177, v76
	ds_bpermute_b32 v93, v177, v77
	ds_bpermute_b32 v94, v177, v78
	ds_bpermute_b32 v95, v177, v79
	ds_bpermute_b32 v96, v177, v80
	ds_bpermute_b32 v97, v177, v81
	s_waitcnt lgkmcnt(7)
	v_add_f32_e32 v74, v74, v90
	s_waitcnt lgkmcnt(6)
	v_add_f32_e32 v75, v75, v91
	s_waitcnt lgkmcnt(5)
	v_add_f32_e32 v76, v76, v92
	s_waitcnt lgkmcnt(4)
	v_add_f32_e32 v77, v77, v93
	s_waitcnt lgkmcnt(3)
	v_add_f32_e32 v78, v78, v94
	s_waitcnt lgkmcnt(2)
	v_add_f32_e32 v79, v79, v95
	s_waitcnt lgkmcnt(1)
	v_add_f32_e32 v80, v80, v96
	s_waitcnt lgkmcnt(0)
	v_add_f32_e32 v81, v81, v97
	ds_bpermute_b32 v82, v178, v66
	ds_bpermute_b32 v83, v178, v67
	ds_bpermute_b32 v84, v178, v68
	ds_bpermute_b32 v85, v178, v69
	ds_bpermute_b32 v86, v178, v70
	ds_bpermute_b32 v87, v178, v71
	ds_bpermute_b32 v88, v178, v72
	ds_bpermute_b32 v89, v178, v73
	s_waitcnt lgkmcnt(7)
	v_add_f32_e32 v66, v66, v82
	s_waitcnt lgkmcnt(6)
	v_add_f32_e32 v67, v67, v83
	s_waitcnt lgkmcnt(5)
	v_add_f32_e32 v68, v68, v84
	s_waitcnt lgkmcnt(4)
	v_add_f32_e32 v69, v69, v85
	s_waitcnt lgkmcnt(3)
	v_add_f32_e32 v70, v70, v86
	s_waitcnt lgkmcnt(2)
	v_add_f32_e32 v71, v71, v87
	s_waitcnt lgkmcnt(1)
	v_add_f32_e32 v72, v72, v88
	s_waitcnt lgkmcnt(0)
	v_add_f32_e32 v73, v73, v89
	ds_bpermute_b32 v90, v178, v74
	ds_bpermute_b32 v91, v178, v75
	ds_bpermute_b32 v92, v178, v76
	ds_bpermute_b32 v93, v178, v77
	ds_bpermute_b32 v94, v178, v78
	ds_bpermute_b32 v95, v178, v79
	ds_bpermute_b32 v96, v178, v80
	ds_bpermute_b32 v97, v178, v81
	s_waitcnt lgkmcnt(7)
	v_add_f32_e32 v74, v74, v90
	s_waitcnt lgkmcnt(6)
	v_add_f32_e32 v75, v75, v91
	s_waitcnt lgkmcnt(5)
	v_add_f32_e32 v76, v76, v92
	s_waitcnt lgkmcnt(4)
	v_add_f32_e32 v77, v77, v93
	s_waitcnt lgkmcnt(3)
	v_add_f32_e32 v78, v78, v94
	s_waitcnt lgkmcnt(2)
	v_add_f32_e32 v79, v79, v95
	s_waitcnt lgkmcnt(1)
	v_add_f32_e32 v80, v80, v96
	s_waitcnt lgkmcnt(0)
	v_add_f32_e32 v81, v81, v97
	ds_bpermute_b32 v82, v179, v66
	ds_bpermute_b32 v83, v179, v67
	ds_bpermute_b32 v84, v179, v68
	ds_bpermute_b32 v85, v179, v69
	ds_bpermute_b32 v86, v179, v70
	ds_bpermute_b32 v87, v179, v71
	ds_bpermute_b32 v88, v179, v72
	ds_bpermute_b32 v89, v179, v73
	s_waitcnt lgkmcnt(7)
	v_add_f32_e32 v66, v66, v82
	s_waitcnt lgkmcnt(6)
	v_add_f32_e32 v67, v67, v83
	s_waitcnt lgkmcnt(5)
	v_add_f32_e32 v68, v68, v84
	s_waitcnt lgkmcnt(4)
	v_add_f32_e32 v69, v69, v85
	s_waitcnt lgkmcnt(3)
	v_add_f32_e32 v70, v70, v86
	s_waitcnt lgkmcnt(2)
	v_add_f32_e32 v71, v71, v87
	s_waitcnt lgkmcnt(1)
	v_add_f32_e32 v72, v72, v88
	s_waitcnt lgkmcnt(0)
	v_add_f32_e32 v73, v73, v89
	ds_bpermute_b32 v90, v179, v74
	ds_bpermute_b32 v91, v179, v75
	ds_bpermute_b32 v92, v179, v76
	ds_bpermute_b32 v93, v179, v77
	ds_bpermute_b32 v94, v179, v78
	ds_bpermute_b32 v95, v179, v79
	ds_bpermute_b32 v96, v179, v80
	ds_bpermute_b32 v97, v179, v81
	s_waitcnt lgkmcnt(7)
	v_add_f32_e32 v74, v74, v90
	s_waitcnt lgkmcnt(6)
	v_add_f32_e32 v75, v75, v91
	s_waitcnt lgkmcnt(5)
	v_add_f32_e32 v76, v76, v92
	s_waitcnt lgkmcnt(4)
	v_add_f32_e32 v77, v77, v93
	s_waitcnt lgkmcnt(3)
	v_add_f32_e32 v78, v78, v94
	s_waitcnt lgkmcnt(2)
	v_add_f32_e32 v79, v79, v95
	s_waitcnt lgkmcnt(1)
	v_add_f32_e32 v80, v80, v96
	s_waitcnt lgkmcnt(0)
	v_add_f32_e32 v81, v81, v97
	ds_bpermute_b32 v82, v180, v66
	ds_bpermute_b32 v83, v180, v67
	ds_bpermute_b32 v84, v180, v68
	ds_bpermute_b32 v85, v180, v69
	ds_bpermute_b32 v86, v180, v70
	ds_bpermute_b32 v87, v180, v71
	ds_bpermute_b32 v88, v180, v72
	ds_bpermute_b32 v89, v180, v73
	s_waitcnt lgkmcnt(7)
	v_add_f32_e32 v66, v66, v82
	s_waitcnt lgkmcnt(6)
	v_add_f32_e32 v67, v67, v83
	s_waitcnt lgkmcnt(5)
	v_add_f32_e32 v68, v68, v84
	s_waitcnt lgkmcnt(4)
	v_add_f32_e32 v69, v69, v85
	s_waitcnt lgkmcnt(3)
	v_add_f32_e32 v70, v70, v86
	s_waitcnt lgkmcnt(2)
	v_add_f32_e32 v71, v71, v87
	s_waitcnt lgkmcnt(1)
	v_add_f32_e32 v72, v72, v88
	s_waitcnt lgkmcnt(0)
	v_add_f32_e32 v73, v73, v89
	ds_bpermute_b32 v90, v180, v74
	ds_bpermute_b32 v91, v180, v75
	ds_bpermute_b32 v92, v180, v76
	ds_bpermute_b32 v93, v180, v77
	ds_bpermute_b32 v94, v180, v78
	ds_bpermute_b32 v95, v180, v79
	ds_bpermute_b32 v96, v180, v80
	ds_bpermute_b32 v97, v180, v81
	s_waitcnt lgkmcnt(7)
	v_add_f32_e32 v74, v74, v90
	s_waitcnt lgkmcnt(6)
	v_add_f32_e32 v75, v75, v91
	s_waitcnt lgkmcnt(5)
	v_add_f32_e32 v76, v76, v92
	s_waitcnt lgkmcnt(4)
	v_add_f32_e32 v77, v77, v93
	s_waitcnt lgkmcnt(3)
	v_add_f32_e32 v78, v78, v94
	s_waitcnt lgkmcnt(2)
	v_add_f32_e32 v79, v79, v95
	s_waitcnt lgkmcnt(1)
	v_add_f32_e32 v80, v80, v96
	s_waitcnt lgkmcnt(0)
	v_add_f32_e32 v81, v81, v97
	ds_bpermute_b32 v82, v163, v66
	ds_bpermute_b32 v83, v163, v67
	ds_bpermute_b32 v84, v163, v68
	ds_bpermute_b32 v85, v163, v69
	ds_bpermute_b32 v86, v163, v70
	ds_bpermute_b32 v87, v163, v71
	ds_bpermute_b32 v88, v163, v72
	ds_bpermute_b32 v89, v163, v73
	s_waitcnt lgkmcnt(7)
	v_add_f32_e32 v66, v66, v82
	s_waitcnt lgkmcnt(6)
	v_add_f32_e32 v67, v67, v83
	s_waitcnt lgkmcnt(5)
	v_add_f32_e32 v68, v68, v84
	s_waitcnt lgkmcnt(4)
	v_add_f32_e32 v69, v69, v85
	s_waitcnt lgkmcnt(3)
	v_add_f32_e32 v70, v70, v86
	s_waitcnt lgkmcnt(2)
	v_add_f32_e32 v71, v71, v87
	s_waitcnt lgkmcnt(1)
	v_add_f32_e32 v72, v72, v88
	s_waitcnt lgkmcnt(0)
	v_add_f32_e32 v73, v73, v89
	ds_bpermute_b32 v90, v163, v74
	ds_bpermute_b32 v91, v163, v75
	ds_bpermute_b32 v92, v163, v76
	ds_bpermute_b32 v93, v163, v77
	ds_bpermute_b32 v94, v163, v78
	ds_bpermute_b32 v95, v163, v79
	ds_bpermute_b32 v96, v163, v80
	ds_bpermute_b32 v97, v163, v81
	s_waitcnt lgkmcnt(7)
	v_add_f32_e32 v74, v74, v90
	s_waitcnt lgkmcnt(6)
	v_add_f32_e32 v75, v75, v91
	s_waitcnt lgkmcnt(5)
	v_add_f32_e32 v76, v76, v92
	s_waitcnt lgkmcnt(4)
	v_add_f32_e32 v77, v77, v93
	s_waitcnt lgkmcnt(3)
	v_add_f32_e32 v78, v78, v94
	s_waitcnt lgkmcnt(2)
	v_add_f32_e32 v79, v79, v95
	s_waitcnt lgkmcnt(1)
	v_add_f32_e32 v80, v80, v96
	s_waitcnt lgkmcnt(0)
	v_add_f32_e32 v81, v81, v97
	v_fmamk_f32 v66, v66, 0x3c000000, v182
	v_fmamk_f32 v67, v67, 0x3c000000, v182
	v_fmamk_f32 v68, v68, 0x3c000000, v182
	v_fmamk_f32 v69, v69, 0x3c000000, v182
	v_fmamk_f32 v70, v70, 0x3c000000, v182
	v_fmamk_f32 v71, v71, 0x3c000000, v182
	v_fmamk_f32 v72, v72, 0x3c000000, v182
	v_fmamk_f32 v73, v73, 0x3c000000, v182
	v_fmamk_f32 v74, v74, 0x3c000000, v182
	v_fmamk_f32 v75, v75, 0x3c000000, v182
	v_fmamk_f32 v76, v76, 0x3c000000, v182
	v_fmamk_f32 v77, v77, 0x3c000000, v182
	v_fmamk_f32 v78, v78, 0x3c000000, v182
	v_fmamk_f32 v79, v79, 0x3c000000, v182
	v_fmamk_f32 v80, v80, 0x3c000000, v182
	v_fmamk_f32 v81, v81, 0x3c000000, v182
	v_rsq_f32_e32 v66, v66
	v_rsq_f32_e32 v67, v67
	v_rsq_f32_e32 v68, v68
	v_rsq_f32_e32 v69, v69
	v_rsq_f32_e32 v70, v70
	v_rsq_f32_e32 v71, v71
	v_rsq_f32_e32 v72, v72
	v_rsq_f32_e32 v73, v73
	v_rsq_f32_e32 v74, v74
	v_rsq_f32_e32 v75, v75
	v_rsq_f32_e32 v76, v76
	v_rsq_f32_e32 v77, v77
	v_rsq_f32_e32 v78, v78
	v_rsq_f32_e32 v79, v79
	v_rsq_f32_e32 v80, v80
	v_rsq_f32_e32 v81, v81
	s_waitcnt vmcnt(0)
	v_mul_f32_e32 v100, 0x3f4ccccd, v100
	v_mul_f32_e32 v101, 0x3f4ccccd, v101
	v_mul_f32_e32 v102, 0x3f4ccccd, v102
	v_mul_f32_e32 v103, 0x3f4ccccd, v103
	s_lshl_b32 s60, s14, 11
	s_lshl_b32 s61, s12, 1
	s_add_i32 s60, s60, s61
	v_lshlrev_b32_e32 v64, 1, v168
	v_lshl_add_u32 v64, v183, 13, v64
	v_add_u32_e32 v64, s60, v64
	s_mov_b32 s60, s3
	s_mov_b32 s61, s30
	v_mul_f32_e32 v0, v0, v66
	v_mul_f32_e32 v16, v16, v66
	v_mul_f32_e32 v32, v32, v66
	v_mul_f32_e32 v48, v48, v66
	v_mul_f32_e32 v0, v100, v0
	v_mul_f32_e32 v16, v101, v16
	v_mul_f32_e32 v32, v102, v32
	v_mul_f32_e32 v48, v103, v48
	v_cvt_pk_bf16_f32 v0, v0, v0
	v_cvt_pk_bf16_f32 v16, v16, v16
	v_cvt_pk_bf16_f32 v32, v32, v32
	v_cvt_pk_bf16_f32 v48, v48, v48
	global_store_short v64, v0, s[60:61]
	global_store_short v64, v16, s[60:61] offset:64
	global_store_short v64, v32, s[60:61] offset:128
	global_store_short v64, v48, s[60:61] offset:192
	v_add_u32_e32 v65, 0x800, v64
	v_mul_f32_e32 v1, v1, v67
	v_mul_f32_e32 v17, v17, v67
	v_mul_f32_e32 v33, v33, v67
	v_mul_f32_e32 v49, v49, v67
	v_mul_f32_e32 v1, v100, v1
	v_mul_f32_e32 v17, v101, v17
	v_mul_f32_e32 v33, v102, v33
	v_mul_f32_e32 v49, v103, v49
	v_cvt_pk_bf16_f32 v1, v1, v1
	v_cvt_pk_bf16_f32 v17, v17, v17
	v_cvt_pk_bf16_f32 v33, v33, v33
	v_cvt_pk_bf16_f32 v49, v49, v49
	global_store_short v65, v1, s[60:61]
	global_store_short v65, v17, s[60:61] offset:64
	global_store_short v65, v33, s[60:61] offset:128
	global_store_short v65, v49, s[60:61] offset:192
	v_add_u32_e32 v65, 0x1000, v64
	v_mul_f32_e32 v2, v2, v68
	v_mul_f32_e32 v18, v18, v68
	v_mul_f32_e32 v34, v34, v68
	v_mul_f32_e32 v50, v50, v68
	v_mul_f32_e32 v2, v100, v2
	v_mul_f32_e32 v18, v101, v18
	v_mul_f32_e32 v34, v102, v34
	v_mul_f32_e32 v50, v103, v50
	v_cvt_pk_bf16_f32 v2, v2, v2
	v_cvt_pk_bf16_f32 v18, v18, v18
	v_cvt_pk_bf16_f32 v34, v34, v34
	v_cvt_pk_bf16_f32 v50, v50, v50
	global_store_short v65, v2, s[60:61]
	global_store_short v65, v18, s[60:61] offset:64
	global_store_short v65, v34, s[60:61] offset:128
	global_store_short v65, v50, s[60:61] offset:192
	v_add_u32_e32 v65, 0x1800, v64
	v_mul_f32_e32 v3, v3, v69
	v_mul_f32_e32 v19, v19, v69
	v_mul_f32_e32 v35, v35, v69
	v_mul_f32_e32 v51, v51, v69
	v_mul_f32_e32 v3, v100, v3
	v_mul_f32_e32 v19, v101, v19
	v_mul_f32_e32 v35, v102, v35
	v_mul_f32_e32 v51, v103, v51
	v_cvt_pk_bf16_f32 v3, v3, v3
	v_cvt_pk_bf16_f32 v19, v19, v19
	v_cvt_pk_bf16_f32 v35, v35, v35
	v_cvt_pk_bf16_f32 v51, v51, v51
	global_store_short v65, v3, s[60:61]
	global_store_short v65, v19, s[60:61] offset:64
	global_store_short v65, v35, s[60:61] offset:128
	global_store_short v65, v51, s[60:61] offset:192
	v_add_u32_e32 v65, 0x4000, v64
	v_mul_f32_e32 v4, v4, v70
	v_mul_f32_e32 v20, v20, v70
	v_mul_f32_e32 v36, v36, v70
	v_mul_f32_e32 v52, v52, v70
	v_mul_f32_e32 v4, v100, v4
	v_mul_f32_e32 v20, v101, v20
	v_mul_f32_e32 v36, v102, v36
	v_mul_f32_e32 v52, v103, v52
	v_cvt_pk_bf16_f32 v4, v4, v4
	v_cvt_pk_bf16_f32 v20, v20, v20
	v_cvt_pk_bf16_f32 v36, v36, v36
	v_cvt_pk_bf16_f32 v52, v52, v52
	global_store_short v65, v4, s[60:61]
	global_store_short v65, v20, s[60:61] offset:64
	global_store_short v65, v36, s[60:61] offset:128
	global_store_short v65, v52, s[60:61] offset:192
	v_add_u32_e32 v65, 0x4800, v64
	v_mul_f32_e32 v5, v5, v71
	v_mul_f32_e32 v21, v21, v71
	v_mul_f32_e32 v37, v37, v71
	v_mul_f32_e32 v53, v53, v71
	v_mul_f32_e32 v5, v100, v5
	v_mul_f32_e32 v21, v101, v21
	v_mul_f32_e32 v37, v102, v37
	v_mul_f32_e32 v53, v103, v53
	v_cvt_pk_bf16_f32 v5, v5, v5
	v_cvt_pk_bf16_f32 v21, v21, v21
	v_cvt_pk_bf16_f32 v37, v37, v37
	v_cvt_pk_bf16_f32 v53, v53, v53
	global_store_short v65, v5, s[60:61]
	global_store_short v65, v21, s[60:61] offset:64
	global_store_short v65, v37, s[60:61] offset:128
	global_store_short v65, v53, s[60:61] offset:192
	v_add_u32_e32 v65, 0x5000, v64
	v_mul_f32_e32 v6, v6, v72
	v_mul_f32_e32 v22, v22, v72
	v_mul_f32_e32 v38, v38, v72
	v_mul_f32_e32 v54, v54, v72
	v_mul_f32_e32 v6, v100, v6
	v_mul_f32_e32 v22, v101, v22
	v_mul_f32_e32 v38, v102, v38
	v_mul_f32_e32 v54, v103, v54
	v_cvt_pk_bf16_f32 v6, v6, v6
	v_cvt_pk_bf16_f32 v22, v22, v22
	v_cvt_pk_bf16_f32 v38, v38, v38
	v_cvt_pk_bf16_f32 v54, v54, v54
	global_store_short v65, v6, s[60:61]
	global_store_short v65, v22, s[60:61] offset:64
	global_store_short v65, v38, s[60:61] offset:128
	global_store_short v65, v54, s[60:61] offset:192
	v_add_u32_e32 v65, 0x5800, v64
	v_mul_f32_e32 v7, v7, v73
	v_mul_f32_e32 v23, v23, v73
	v_mul_f32_e32 v39, v39, v73
	v_mul_f32_e32 v55, v55, v73
	v_mul_f32_e32 v7, v100, v7
	v_mul_f32_e32 v23, v101, v23
	v_mul_f32_e32 v39, v102, v39
	v_mul_f32_e32 v55, v103, v55
	v_cvt_pk_bf16_f32 v7, v7, v7
	v_cvt_pk_bf16_f32 v23, v23, v23
	v_cvt_pk_bf16_f32 v39, v39, v39
	v_cvt_pk_bf16_f32 v55, v55, v55
	global_store_short v65, v7, s[60:61]
	global_store_short v65, v23, s[60:61] offset:64
	global_store_short v65, v39, s[60:61] offset:128
	global_store_short v65, v55, s[60:61] offset:192
	v_add_u32_e32 v65, 0x8000, v64
	v_mul_f32_e32 v8, v8, v74
	v_mul_f32_e32 v24, v24, v74
	v_mul_f32_e32 v40, v40, v74
	v_mul_f32_e32 v56, v56, v74
	v_mul_f32_e32 v8, v100, v8
	v_mul_f32_e32 v24, v101, v24
	v_mul_f32_e32 v40, v102, v40
	v_mul_f32_e32 v56, v103, v56
	v_cvt_pk_bf16_f32 v8, v8, v8
	v_cvt_pk_bf16_f32 v24, v24, v24
	v_cvt_pk_bf16_f32 v40, v40, v40
	v_cvt_pk_bf16_f32 v56, v56, v56
	global_store_short v65, v8, s[60:61]
	global_store_short v65, v24, s[60:61] offset:64
	global_store_short v65, v40, s[60:61] offset:128
	global_store_short v65, v56, s[60:61] offset:192
	v_add_u32_e32 v65, 0x8800, v64
	v_mul_f32_e32 v9, v9, v75
	v_mul_f32_e32 v25, v25, v75
	v_mul_f32_e32 v41, v41, v75
	v_mul_f32_e32 v57, v57, v75
	v_mul_f32_e32 v9, v100, v9
	v_mul_f32_e32 v25, v101, v25
	v_mul_f32_e32 v41, v102, v41
	v_mul_f32_e32 v57, v103, v57
	v_cvt_pk_bf16_f32 v9, v9, v9
	v_cvt_pk_bf16_f32 v25, v25, v25
	v_cvt_pk_bf16_f32 v41, v41, v41
	v_cvt_pk_bf16_f32 v57, v57, v57
	global_store_short v65, v9, s[60:61]
	global_store_short v65, v25, s[60:61] offset:64
	global_store_short v65, v41, s[60:61] offset:128
	global_store_short v65, v57, s[60:61] offset:192
	v_add_u32_e32 v65, 0x9000, v64
	v_mul_f32_e32 v10, v10, v76
	v_mul_f32_e32 v26, v26, v76
	v_mul_f32_e32 v42, v42, v76
	v_mul_f32_e32 v58, v58, v76
	v_mul_f32_e32 v10, v100, v10
	v_mul_f32_e32 v26, v101, v26
	v_mul_f32_e32 v42, v102, v42
	v_mul_f32_e32 v58, v103, v58
	v_cvt_pk_bf16_f32 v10, v10, v10
	v_cvt_pk_bf16_f32 v26, v26, v26
	v_cvt_pk_bf16_f32 v42, v42, v42
	v_cvt_pk_bf16_f32 v58, v58, v58
	global_store_short v65, v10, s[60:61]
	global_store_short v65, v26, s[60:61] offset:64
	global_store_short v65, v42, s[60:61] offset:128
	global_store_short v65, v58, s[60:61] offset:192
	v_add_u32_e32 v65, 0x9800, v64
	v_mul_f32_e32 v11, v11, v77
	v_mul_f32_e32 v27, v27, v77
	v_mul_f32_e32 v43, v43, v77
	v_mul_f32_e32 v59, v59, v77
	v_mul_f32_e32 v11, v100, v11
	v_mul_f32_e32 v27, v101, v27
	v_mul_f32_e32 v43, v102, v43
	v_mul_f32_e32 v59, v103, v59
	v_cvt_pk_bf16_f32 v11, v11, v11
	v_cvt_pk_bf16_f32 v27, v27, v27
	v_cvt_pk_bf16_f32 v43, v43, v43
	v_cvt_pk_bf16_f32 v59, v59, v59
	global_store_short v65, v11, s[60:61]
	global_store_short v65, v27, s[60:61] offset:64
	global_store_short v65, v43, s[60:61] offset:128
	global_store_short v65, v59, s[60:61] offset:192
	v_add_u32_e32 v65, 0xc000, v64
	v_mul_f32_e32 v12, v12, v78
	v_mul_f32_e32 v28, v28, v78
	v_mul_f32_e32 v44, v44, v78
	v_mul_f32_e32 v60, v60, v78
	v_mul_f32_e32 v12, v100, v12
	v_mul_f32_e32 v28, v101, v28
	v_mul_f32_e32 v44, v102, v44
	v_mul_f32_e32 v60, v103, v60
	v_cvt_pk_bf16_f32 v12, v12, v12
	v_cvt_pk_bf16_f32 v28, v28, v28
	v_cvt_pk_bf16_f32 v44, v44, v44
	v_cvt_pk_bf16_f32 v60, v60, v60
	global_store_short v65, v12, s[60:61]
	global_store_short v65, v28, s[60:61] offset:64
	global_store_short v65, v44, s[60:61] offset:128
	global_store_short v65, v60, s[60:61] offset:192
	v_add_u32_e32 v65, 0xc800, v64
	v_mul_f32_e32 v13, v13, v79
	v_mul_f32_e32 v29, v29, v79
	v_mul_f32_e32 v45, v45, v79
	v_mul_f32_e32 v61, v61, v79
	v_mul_f32_e32 v13, v100, v13
	v_mul_f32_e32 v29, v101, v29
	v_mul_f32_e32 v45, v102, v45
	v_mul_f32_e32 v61, v103, v61
	v_cvt_pk_bf16_f32 v13, v13, v13
	v_cvt_pk_bf16_f32 v29, v29, v29
	v_cvt_pk_bf16_f32 v45, v45, v45
	v_cvt_pk_bf16_f32 v61, v61, v61
	global_store_short v65, v13, s[60:61]
	global_store_short v65, v29, s[60:61] offset:64
	global_store_short v65, v45, s[60:61] offset:128
	global_store_short v65, v61, s[60:61] offset:192
	v_add_u32_e32 v65, 0xd000, v64
	v_mul_f32_e32 v14, v14, v80
	v_mul_f32_e32 v30, v30, v80
	v_mul_f32_e32 v46, v46, v80
	v_mul_f32_e32 v62, v62, v80
	v_mul_f32_e32 v14, v100, v14
	v_mul_f32_e32 v30, v101, v30
	v_mul_f32_e32 v46, v102, v46
	v_mul_f32_e32 v62, v103, v62
	v_cvt_pk_bf16_f32 v14, v14, v14
	v_cvt_pk_bf16_f32 v30, v30, v30
	v_cvt_pk_bf16_f32 v46, v46, v46
	v_cvt_pk_bf16_f32 v62, v62, v62
	global_store_short v65, v14, s[60:61]
	global_store_short v65, v30, s[60:61] offset:64
	global_store_short v65, v46, s[60:61] offset:128
	global_store_short v65, v62, s[60:61] offset:192
	v_add_u32_e32 v65, 0xd800, v64
	v_mul_f32_e32 v15, v15, v81
	v_mul_f32_e32 v31, v31, v81
	v_mul_f32_e32 v47, v47, v81
	v_mul_f32_e32 v63, v63, v81
	v_mul_f32_e32 v15, v100, v15
	v_mul_f32_e32 v31, v101, v31
	v_mul_f32_e32 v47, v102, v47
	v_mul_f32_e32 v63, v103, v63
	v_cvt_pk_bf16_f32 v15, v15, v15
	v_cvt_pk_bf16_f32 v31, v31, v31
	v_cvt_pk_bf16_f32 v47, v47, v47
	v_cvt_pk_bf16_f32 v63, v63, v63
	global_store_short v65, v15, s[60:61]
	global_store_short v65, v31, s[60:61] offset:64
	global_store_short v65, v47, s[60:61] offset:128
	global_store_short v65, v63, s[60:61] offset:192
	v_mov_b32_e32 v242, v246
	v_mov_b32_e32 v243, v247
	s_mov_b32 m0, vcc_hi
	s_add_i32 s77, s77, s74
	s_cmpk_lt_i32 s77, 0x200
	s_waitcnt vmcnt(0) lgkmcnt(0)
	s_barrier
	s_cbranch_scc1 .LBB0_209
